# adds hand-written SwiGLU epilogue (a*g times rcp(1+exp2(a*(-log2e*rstd))) times rstd^2, fewer VALU ops) on top of pipelined RES/MERGE/STORE epilogues and x-conversion loop
# speedup vs baseline: 1.0015x; 1.0015x over previous
; #define GAS __attribute__((address_space(1)))
; __device__ __forceinline__ u32x4 pack8(f32x4 a, f32x4 b) { u32x4 w; w.x = cvtpk(a[0], a[1]); w.y = cvtpk(a[2], a[3]); w.z = cvtpk(b[0], b[1]); w.w = cvtpk(b[2], b[3]); return w; }
; __device__ __forceinline__ f32x4 sig4(f32x4 x) { f32x4 r; r[0] = fsigmoid(x[0]); r[1] = fsigmoid(x[1]); r[2] = fsigmoid(x[2]); r[3] = fsigmoid(x[3]); return r; }
;     __device__ __forceinline__ void operator()(const f32x4 (&acc)[2][2][4][2], const Unit& u, int wr, int wc, int fr, int fq) const {
;     ...
;         if (mode == EM_SWIGLU) {
;             const int colh = u.pn * 128 + wc * 32 + fq * 8;
;             float rsv[2][4];
; #pragma unroll
;             for (int ai = 0; ai < 2; ++ai)
; #pragma unroll
;                 for (int m = 0; m < 4; ++m) rsv[ai][m] = ssq_in[rowb + ai * HALF + m * 16];
; #pragma unroll
;             for (int ai = 0; ai < 2; ++ai)
; #pragma unroll
;                 for (int m = 0; m < 4; ++m) {
;                     const int row = rowb + ai * HALF + m * 16;
;                     const float rstd = __builtin_amdgcn_rsqf(rsv[ai][m] * (1.0f / DM) + EPS);
;                     f32x4 o[2];
; #pragma unroll
;                     for (int n = 0; n < 2; ++n) { const f32x4 a = acc[ai][0][m][n] * rstd, g = acc[ai][1][m][n] * rstd; o[n] = a * sig4(a) * g; }
;                     *(GAS u32x4*)(o16 + (size_t)row * DFF + colh) = pack8(o[0], o[1]);
;                 }
.Lswiglu_fast:
	s_waitcnt lgkmcnt(0)
	v_lshlrev_b32_e32 v188, 2, v182
	global_load_dword v142, v188, s[12:13]
	global_load_dword v143, v188, s[12:13] offset:64
	global_load_dword v144, v188, s[12:13] offset:128
	global_load_dword v145, v188, s[12:13] offset:192
	global_load_dword v146, v188, s[12:13] offset:512
	global_load_dword v147, v188, s[12:13] offset:576
	global_load_dword v148, v188, s[12:13] offset:640
	global_load_dword v149, v188, s[12:13] offset:704
	v_mul_u32_u24_e32 v156, 0x1600, v182
	s_lshl_b32 s0, s67, 8
	v_lshl_add_u32 v156, v176, 1, v156
	v_add_u32_e32 v156, s0, v156
	v_mov_b32_e32 v154, 1.0
	v_mov_b32_e32 v155, 1.0
	s_waitcnt vmcnt(7)
	v_fmamk_f32 v189, v142, 0x3a800000, v210
	v_rsq_f32_e32 v189, v189
	v_pk_mul_f32 v[122:123], v[114:115], v[122:123]
	v_pk_mul_f32 v[124:125], v[116:117], v[124:125]
	v_pk_mul_f32 v[118:119], v[126:127], v[118:119]
	v_pk_mul_f32 v[120:121], v[128:129], v[120:121]
	v_mul_f32_e32 v150, 0xbfb8aa3b, v189
	v_mul_f32_e32 v152, v189, v189
	v_pk_mul_f32 v[130:131], v[114:115], v[150:151] op_sel_hi:[1,0]
	v_pk_mul_f32 v[132:133], v[116:117], v[150:151] op_sel_hi:[1,0]
	v_pk_mul_f32 v[134:135], v[126:127], v[150:151] op_sel_hi:[1,0]
	v_pk_mul_f32 v[136:137], v[128:129], v[150:151] op_sel_hi:[1,0]
	v_exp_f32_e32 v130, v130
	v_exp_f32_e32 v131, v131
	v_exp_f32_e32 v132, v132
	v_exp_f32_e32 v133, v133
	v_exp_f32_e32 v134, v134
	v_exp_f32_e32 v135, v135
	v_exp_f32_e32 v136, v136
	v_exp_f32_e32 v137, v137
	v_pk_add_f32 v[130:131], v[130:131], v[154:155]
	v_pk_add_f32 v[132:133], v[132:133], v[154:155]
	v_pk_add_f32 v[134:135], v[134:135], v[154:155]
	v_pk_add_f32 v[136:137], v[136:137], v[154:155]
	v_rcp_f32_e32 v130, v130
	v_rcp_f32_e32 v131, v131
	v_rcp_f32_e32 v132, v132
	v_rcp_f32_e32 v133, v133
	v_rcp_f32_e32 v134, v134
	v_rcp_f32_e32 v135, v135
	v_rcp_f32_e32 v136, v136
	v_rcp_f32_e32 v137, v137
	v_pk_mul_f32 v[130:131], v[130:131], v[152:153] op_sel_hi:[1,0]
	v_pk_mul_f32 v[132:133], v[132:133], v[152:153] op_sel_hi:[1,0]
	v_pk_mul_f32 v[134:135], v[134:135], v[152:153] op_sel_hi:[1,0]
	v_pk_mul_f32 v[136:137], v[136:137], v[152:153] op_sel_hi:[1,0]
	v_pk_mul_f32 v[122:123], v[122:123], v[130:131]
	v_pk_mul_f32 v[124:125], v[124:125], v[132:133]
	v_pk_mul_f32 v[118:119], v[118:119], v[134:135]
	v_pk_mul_f32 v[120:121], v[120:121], v[136:137]
	v_mov_b32_e32 v157, v156
	v_cvt_pk_bf16_f32 v138, v122, v123
	v_cvt_pk_bf16_f32 v139, v124, v125
	v_cvt_pk_bf16_f32 v140, v118, v119
	v_cvt_pk_bf16_f32 v141, v120, v121
	global_store_dwordx4 v157, v[138:141], s[18:19]
	s_waitcnt vmcnt(7)
	v_fmamk_f32 v189, v143, 0x3a800000, v210
	v_rsq_f32_e32 v189, v189
	v_pk_mul_f32 v[106:107], v[110:111], v[106:107]
	v_pk_mul_f32 v[108:109], v[112:113], v[108:109]
	v_pk_mul_f32 v[98:99], v[102:103], v[98:99]
	v_pk_mul_f32 v[100:101], v[104:105], v[100:101]
	v_mul_f32_e32 v150, 0xbfb8aa3b, v189
	v_mul_f32_e32 v152, v189, v189
	v_pk_mul_f32 v[130:131], v[110:111], v[150:151] op_sel_hi:[1,0]
	v_pk_mul_f32 v[132:133], v[112:113], v[150:151] op_sel_hi:[1,0]
	v_pk_mul_f32 v[134:135], v[102:103], v[150:151] op_sel_hi:[1,0]
	v_pk_mul_f32 v[136:137], v[104:105], v[150:151] op_sel_hi:[1,0]
	v_exp_f32_e32 v130, v130
	v_exp_f32_e32 v131, v131
	v_exp_f32_e32 v132, v132
	v_exp_f32_e32 v133, v133
	v_exp_f32_e32 v134, v134
	v_exp_f32_e32 v135, v135
	v_exp_f32_e32 v136, v136
	v_exp_f32_e32 v137, v137
	v_pk_add_f32 v[130:131], v[130:131], v[154:155]
	v_pk_add_f32 v[132:133], v[132:133], v[154:155]
	v_pk_add_f32 v[134:135], v[134:135], v[154:155]
	v_pk_add_f32 v[136:137], v[136:137], v[154:155]
	v_rcp_f32_e32 v130, v130
	v_rcp_f32_e32 v131, v131
	v_rcp_f32_e32 v132, v132
	v_rcp_f32_e32 v133, v133
	v_rcp_f32_e32 v134, v134
	v_rcp_f32_e32 v135, v135
	v_rcp_f32_e32 v136, v136
	v_rcp_f32_e32 v137, v137
	v_pk_mul_f32 v[130:131], v[130:131], v[152:153] op_sel_hi:[1,0]
	v_pk_mul_f32 v[132:133], v[132:133], v[152:153] op_sel_hi:[1,0]
	v_pk_mul_f32 v[134:135], v[134:135], v[152:153] op_sel_hi:[1,0]
	v_pk_mul_f32 v[136:137], v[136:137], v[152:153] op_sel_hi:[1,0]
	v_pk_mul_f32 v[106:107], v[106:107], v[130:131]
	v_pk_mul_f32 v[108:109], v[108:109], v[132:133]
	v_pk_mul_f32 v[98:99], v[98:99], v[134:135]
	v_pk_mul_f32 v[100:101], v[100:101], v[136:137]
	v_add_u32_e32 v157, 0x16000, v156
	v_cvt_pk_bf16_f32 v184, v106, v107
	v_cvt_pk_bf16_f32 v185, v108, v109
	v_cvt_pk_bf16_f32 v186, v98, v99
	v_cvt_pk_bf16_f32 v187, v100, v101
	global_store_dwordx4 v157, v[184:187], s[18:19]
	s_waitcnt vmcnt(7)
	v_fmamk_f32 v189, v144, 0x3a800000, v210
	v_rsq_f32_e32 v189, v189
	v_pk_mul_f32 v[90:91], v[94:95], v[90:91]
	v_pk_mul_f32 v[92:93], v[96:97], v[92:93]
	v_pk_mul_f32 v[82:83], v[86:87], v[82:83]
	v_pk_mul_f32 v[84:85], v[88:89], v[84:85]
	v_mul_f32_e32 v150, 0xbfb8aa3b, v189
	v_mul_f32_e32 v152, v189, v189
	v_pk_mul_f32 v[130:131], v[94:95], v[150:151] op_sel_hi:[1,0]
	v_pk_mul_f32 v[132:133], v[96:97], v[150:151] op_sel_hi:[1,0]
	v_pk_mul_f32 v[134:135], v[86:87], v[150:151] op_sel_hi:[1,0]
	v_pk_mul_f32 v[136:137], v[88:89], v[150:151] op_sel_hi:[1,0]
	v_exp_f32_e32 v130, v130
	v_exp_f32_e32 v131, v131
	v_exp_f32_e32 v132, v132
	v_exp_f32_e32 v133, v133
	v_exp_f32_e32 v134, v134
	v_exp_f32_e32 v135, v135
	v_exp_f32_e32 v136, v136
	v_exp_f32_e32 v137, v137
	v_pk_add_f32 v[130:131], v[130:131], v[154:155]
	v_pk_add_f32 v[132:133], v[132:133], v[154:155]
	v_pk_add_f32 v[134:135], v[134:135], v[154:155]
	v_pk_add_f32 v[136:137], v[136:137], v[154:155]
	v_rcp_f32_e32 v130, v130
	v_rcp_f32_e32 v131, v131
	v_rcp_f32_e32 v132, v132
	v_rcp_f32_e32 v133, v133
	v_rcp_f32_e32 v134, v134
	v_rcp_f32_e32 v135, v135
	v_rcp_f32_e32 v136, v136
	v_rcp_f32_e32 v137, v137
	v_pk_mul_f32 v[130:131], v[130:131], v[152:153] op_sel_hi:[1,0]
	v_pk_mul_f32 v[132:133], v[132:133], v[152:153] op_sel_hi:[1,0]
	v_pk_mul_f32 v[134:135], v[134:135], v[152:153] op_sel_hi:[1,0]
	v_pk_mul_f32 v[136:137], v[136:137], v[152:153] op_sel_hi:[1,0]
	v_pk_mul_f32 v[90:91], v[90:91], v[130:131]
	v_pk_mul_f32 v[92:93], v[92:93], v[132:133]
	v_pk_mul_f32 v[82:83], v[82:83], v[134:135]
	v_pk_mul_f32 v[84:85], v[84:85], v[136:137]
	v_add_u32_e32 v157, 0x2c000, v156
	v_cvt_pk_bf16_f32 v138, v90, v91
	v_cvt_pk_bf16_f32 v139, v92, v93
	v_cvt_pk_bf16_f32 v140, v82, v83
	v_cvt_pk_bf16_f32 v141, v84, v85
	global_store_dwordx4 v157, v[138:141], s[18:19]
	s_waitcnt vmcnt(7)
; #define GAS __attribute__((address_space(1)))
; __device__ __forceinline__ u32x4 pack8(f32x4 a, f32x4 b) { u32x4 w; w.x = cvtpk(a[0], a[1]); w.y = cvtpk(a[2], a[3]); w.z = cvtpk(b[0], b[1]); w.w = cvtpk(b[2], b[3]); return w; }
; __device__ __forceinline__ f32x4 sig4(f32x4 x) { f32x4 r; r[0] = fsigmoid(x[0]); r[1] = fsigmoid(x[1]); r[2] = fsigmoid(x[2]); r[3] = fsigmoid(x[3]); return r; }
;     __device__ __forceinline__ void operator()(const f32x4 (&acc)[2][2][4][2], const Unit& u, int wr, int wc, int fr, int fq) const {
;     ...
;             for (int ai = 0; ai < 2; ++ai)
; #pragma unroll
;                 for (int m = 0; m < 4; ++m) {
;                     const int row = rowb + ai * HALF + m * 16;
;                     const float rstd = __builtin_amdgcn_rsqf(rsv[ai][m] * (1.0f / DM) + EPS);
;                     f32x4 o[2];
; #pragma unroll
;                     for (int n = 0; n < 2; ++n) { const f32x4 a = acc[ai][0][m][n] * rstd, g = acc[ai][1][m][n] * rstd; o[n] = a * sig4(a) * g; }
;                     *(GAS u32x4*)(o16 + (size_t)row * DFF + colh) = pack8(o[0], o[1]);
;                 }
	v_fmamk_f32 v189, v145, 0x3a800000, v210
	v_rsq_f32_e32 v189, v189
	v_pk_mul_f32 v[74:75], v[78:79], v[74:75]
	v_pk_mul_f32 v[76:77], v[80:81], v[76:77]
	v_pk_mul_f32 v[66:67], v[70:71], v[66:67]
	v_pk_mul_f32 v[68:69], v[72:73], v[68:69]
	v_mul_f32_e32 v150, 0xbfb8aa3b, v189
	v_mul_f32_e32 v152, v189, v189
	v_pk_mul_f32 v[130:131], v[78:79], v[150:151] op_sel_hi:[1,0]
	v_pk_mul_f32 v[132:133], v[80:81], v[150:151] op_sel_hi:[1,0]
	v_pk_mul_f32 v[134:135], v[70:71], v[150:151] op_sel_hi:[1,0]
	v_pk_mul_f32 v[136:137], v[72:73], v[150:151] op_sel_hi:[1,0]
	v_exp_f32_e32 v130, v130
	v_exp_f32_e32 v131, v131
	v_exp_f32_e32 v132, v132
	v_exp_f32_e32 v133, v133
	v_exp_f32_e32 v134, v134
	v_exp_f32_e32 v135, v135
	v_exp_f32_e32 v136, v136
	v_exp_f32_e32 v137, v137
	v_pk_add_f32 v[130:131], v[130:131], v[154:155]
	v_pk_add_f32 v[132:133], v[132:133], v[154:155]
	v_pk_add_f32 v[134:135], v[134:135], v[154:155]
	v_pk_add_f32 v[136:137], v[136:137], v[154:155]
	v_rcp_f32_e32 v130, v130
	v_rcp_f32_e32 v131, v131
	v_rcp_f32_e32 v132, v132
	v_rcp_f32_e32 v133, v133
	v_rcp_f32_e32 v134, v134
	v_rcp_f32_e32 v135, v135
	v_rcp_f32_e32 v136, v136
	v_rcp_f32_e32 v137, v137
	v_pk_mul_f32 v[130:131], v[130:131], v[152:153] op_sel_hi:[1,0]
	v_pk_mul_f32 v[132:133], v[132:133], v[152:153] op_sel_hi:[1,0]
	v_pk_mul_f32 v[134:135], v[134:135], v[152:153] op_sel_hi:[1,0]
	v_pk_mul_f32 v[136:137], v[136:137], v[152:153] op_sel_hi:[1,0]
	v_pk_mul_f32 v[74:75], v[74:75], v[130:131]
	v_pk_mul_f32 v[76:77], v[76:77], v[132:133]
	v_pk_mul_f32 v[66:67], v[66:67], v[134:135]
	v_pk_mul_f32 v[68:69], v[68:69], v[136:137]
	v_add_u32_e32 v157, 0x42000, v156
	v_cvt_pk_bf16_f32 v184, v74, v75
	v_cvt_pk_bf16_f32 v185, v76, v77
	v_cvt_pk_bf16_f32 v186, v66, v67
	v_cvt_pk_bf16_f32 v187, v68, v69
	global_store_dwordx4 v157, v[184:187], s[18:19]
	s_waitcnt vmcnt(7)
	v_fmamk_f32 v189, v146, 0x3a800000, v210
	v_rsq_f32_e32 v189, v189
	v_pk_mul_f32 v[58:59], v[62:63], v[58:59]
	v_pk_mul_f32 v[60:61], v[64:65], v[60:61]
	v_pk_mul_f32 v[50:51], v[54:55], v[50:51]
	v_pk_mul_f32 v[52:53], v[56:57], v[52:53]
	v_mul_f32_e32 v150, 0xbfb8aa3b, v189
	v_mul_f32_e32 v152, v189, v189
	v_pk_mul_f32 v[130:131], v[62:63], v[150:151] op_sel_hi:[1,0]
	v_pk_mul_f32 v[132:133], v[64:65], v[150:151] op_sel_hi:[1,0]
	v_pk_mul_f32 v[134:135], v[54:55], v[150:151] op_sel_hi:[1,0]
	v_pk_mul_f32 v[136:137], v[56:57], v[150:151] op_sel_hi:[1,0]
	v_exp_f32_e32 v130, v130
	v_exp_f32_e32 v131, v131
	v_exp_f32_e32 v132, v132
	v_exp_f32_e32 v133, v133
	v_exp_f32_e32 v134, v134
	v_exp_f32_e32 v135, v135
	v_exp_f32_e32 v136, v136
	v_exp_f32_e32 v137, v137
	v_pk_add_f32 v[130:131], v[130:131], v[154:155]
	v_pk_add_f32 v[132:133], v[132:133], v[154:155]
	v_pk_add_f32 v[134:135], v[134:135], v[154:155]
	v_pk_add_f32 v[136:137], v[136:137], v[154:155]
	v_rcp_f32_e32 v130, v130
	v_rcp_f32_e32 v131, v131
	v_rcp_f32_e32 v132, v132
	v_rcp_f32_e32 v133, v133
	v_rcp_f32_e32 v134, v134
	v_rcp_f32_e32 v135, v135
	v_rcp_f32_e32 v136, v136
	v_rcp_f32_e32 v137, v137
	v_pk_mul_f32 v[130:131], v[130:131], v[152:153] op_sel_hi:[1,0]
	v_pk_mul_f32 v[132:133], v[132:133], v[152:153] op_sel_hi:[1,0]
	v_pk_mul_f32 v[134:135], v[134:135], v[152:153] op_sel_hi:[1,0]
	v_pk_mul_f32 v[136:137], v[136:137], v[152:153] op_sel_hi:[1,0]
	v_pk_mul_f32 v[58:59], v[58:59], v[130:131]
	v_pk_mul_f32 v[60:61], v[60:61], v[132:133]
	v_pk_mul_f32 v[50:51], v[50:51], v[134:135]
	v_pk_mul_f32 v[52:53], v[52:53], v[136:137]
	v_add_u32_e32 v157, 0xb0000, v156
	v_cvt_pk_bf16_f32 v138, v58, v59
	v_cvt_pk_bf16_f32 v139, v60, v61
	v_cvt_pk_bf16_f32 v140, v50, v51
	v_cvt_pk_bf16_f32 v141, v52, v53
	global_store_dwordx4 v157, v[138:141], s[18:19]
	s_waitcnt vmcnt(7)
; #define GAS __attribute__((address_space(1)))
; __device__ __forceinline__ u32x4 pack8(f32x4 a, f32x4 b) { u32x4 w; w.x = cvtpk(a[0], a[1]); w.y = cvtpk(a[2], a[3]); w.z = cvtpk(b[0], b[1]); w.w = cvtpk(b[2], b[3]); return w; }
; __device__ __forceinline__ f32x4 sig4(f32x4 x) { f32x4 r; r[0] = fsigmoid(x[0]); r[1] = fsigmoid(x[1]); r[2] = fsigmoid(x[2]); r[3] = fsigmoid(x[3]); return r; }
;     __device__ __forceinline__ void operator()(const f32x4 (&acc)[2][2][4][2], const Unit& u, int wr, int wc, int fr, int fq) const {
;     ...
;             for (int ai = 0; ai < 2; ++ai)
; #pragma unroll
;                 for (int m = 0; m < 4; ++m) {
;                     const int row = rowb + ai * HALF + m * 16;
;                     const float rstd = __builtin_amdgcn_rsqf(rsv[ai][m] * (1.0f / DM) + EPS);
;                     f32x4 o[2];
; #pragma unroll
;                     for (int n = 0; n < 2; ++n) { const f32x4 a = acc[ai][0][m][n] * rstd, g = acc[ai][1][m][n] * rstd; o[n] = a * sig4(a) * g; }
;                     *(GAS u32x4*)(o16 + (size_t)row * DFF + colh) = pack8(o[0], o[1]);
;                 }
	v_fmamk_f32 v189, v147, 0x3a800000, v210
	v_rsq_f32_e32 v189, v189
	v_pk_mul_f32 v[42:43], v[46:47], v[42:43]
	v_pk_mul_f32 v[44:45], v[48:49], v[44:45]
	v_pk_mul_f32 v[34:35], v[38:39], v[34:35]
	v_pk_mul_f32 v[36:37], v[40:41], v[36:37]
	v_mul_f32_e32 v150, 0xbfb8aa3b, v189
	v_mul_f32_e32 v152, v189, v189
	v_pk_mul_f32 v[130:131], v[46:47], v[150:151] op_sel_hi:[1,0]
	v_pk_mul_f32 v[132:133], v[48:49], v[150:151] op_sel_hi:[1,0]
	v_pk_mul_f32 v[134:135], v[38:39], v[150:151] op_sel_hi:[1,0]
	v_pk_mul_f32 v[136:137], v[40:41], v[150:151] op_sel_hi:[1,0]
	v_exp_f32_e32 v130, v130
	v_exp_f32_e32 v131, v131
	v_exp_f32_e32 v132, v132
	v_exp_f32_e32 v133, v133
	v_exp_f32_e32 v134, v134
	v_exp_f32_e32 v135, v135
	v_exp_f32_e32 v136, v136
	v_exp_f32_e32 v137, v137
	v_pk_add_f32 v[130:131], v[130:131], v[154:155]
	v_pk_add_f32 v[132:133], v[132:133], v[154:155]
	v_pk_add_f32 v[134:135], v[134:135], v[154:155]
	v_pk_add_f32 v[136:137], v[136:137], v[154:155]
	v_rcp_f32_e32 v130, v130
	v_rcp_f32_e32 v131, v131
	v_rcp_f32_e32 v132, v132
	v_rcp_f32_e32 v133, v133
	v_rcp_f32_e32 v134, v134
	v_rcp_f32_e32 v135, v135
	v_rcp_f32_e32 v136, v136
	v_rcp_f32_e32 v137, v137
	v_pk_mul_f32 v[130:131], v[130:131], v[152:153] op_sel_hi:[1,0]
	v_pk_mul_f32 v[132:133], v[132:133], v[152:153] op_sel_hi:[1,0]
	v_pk_mul_f32 v[134:135], v[134:135], v[152:153] op_sel_hi:[1,0]
	v_pk_mul_f32 v[136:137], v[136:137], v[152:153] op_sel_hi:[1,0]
	v_pk_mul_f32 v[42:43], v[42:43], v[130:131]
	v_pk_mul_f32 v[44:45], v[44:45], v[132:133]
	v_pk_mul_f32 v[34:35], v[34:35], v[134:135]
	v_pk_mul_f32 v[36:37], v[36:37], v[136:137]
	v_add_u32_e32 v157, 0xc6000, v156
	v_cvt_pk_bf16_f32 v184, v42, v43
	v_cvt_pk_bf16_f32 v185, v44, v45
	v_cvt_pk_bf16_f32 v186, v34, v35
	v_cvt_pk_bf16_f32 v187, v36, v37
	global_store_dwordx4 v157, v[184:187], s[18:19]
	s_waitcnt vmcnt(7)
	v_fmamk_f32 v189, v148, 0x3a800000, v210
	v_rsq_f32_e32 v189, v189
	v_pk_mul_f32 v[26:27], v[30:31], v[26:27]
	v_pk_mul_f32 v[28:29], v[32:33], v[28:29]
	v_pk_mul_f32 v[18:19], v[22:23], v[18:19]
	v_pk_mul_f32 v[20:21], v[24:25], v[20:21]
	v_mul_f32_e32 v150, 0xbfb8aa3b, v189
	v_mul_f32_e32 v152, v189, v189
	v_pk_mul_f32 v[130:131], v[30:31], v[150:151] op_sel_hi:[1,0]
	v_pk_mul_f32 v[132:133], v[32:33], v[150:151] op_sel_hi:[1,0]
	v_pk_mul_f32 v[134:135], v[22:23], v[150:151] op_sel_hi:[1,0]
	v_pk_mul_f32 v[136:137], v[24:25], v[150:151] op_sel_hi:[1,0]
	v_exp_f32_e32 v130, v130
	v_exp_f32_e32 v131, v131
	v_exp_f32_e32 v132, v132
	v_exp_f32_e32 v133, v133
	v_exp_f32_e32 v134, v134
	v_exp_f32_e32 v135, v135
	v_exp_f32_e32 v136, v136
	v_exp_f32_e32 v137, v137
	v_pk_add_f32 v[130:131], v[130:131], v[154:155]
	v_pk_add_f32 v[132:133], v[132:133], v[154:155]
	v_pk_add_f32 v[134:135], v[134:135], v[154:155]
	v_pk_add_f32 v[136:137], v[136:137], v[154:155]
	v_rcp_f32_e32 v130, v130
	v_rcp_f32_e32 v131, v131
	v_rcp_f32_e32 v132, v132
	v_rcp_f32_e32 v133, v133
	v_rcp_f32_e32 v134, v134
	v_rcp_f32_e32 v135, v135
	v_rcp_f32_e32 v136, v136
	v_rcp_f32_e32 v137, v137
	v_pk_mul_f32 v[130:131], v[130:131], v[152:153] op_sel_hi:[1,0]
	v_pk_mul_f32 v[132:133], v[132:133], v[152:153] op_sel_hi:[1,0]
	v_pk_mul_f32 v[134:135], v[134:135], v[152:153] op_sel_hi:[1,0]
	v_pk_mul_f32 v[136:137], v[136:137], v[152:153] op_sel_hi:[1,0]
	v_pk_mul_f32 v[26:27], v[26:27], v[130:131]
	v_pk_mul_f32 v[28:29], v[28:29], v[132:133]
	v_pk_mul_f32 v[18:19], v[18:19], v[134:135]
	v_pk_mul_f32 v[20:21], v[20:21], v[136:137]
	v_add_u32_e32 v157, 0xdc000, v156
	v_cvt_pk_bf16_f32 v138, v26, v27
	v_cvt_pk_bf16_f32 v139, v28, v29
	v_cvt_pk_bf16_f32 v140, v18, v19
	v_cvt_pk_bf16_f32 v141, v20, v21
	global_store_dwordx4 v157, v[138:141], s[18:19]
	s_waitcnt vmcnt(7)
	v_fmamk_f32 v189, v149, 0x3a800000, v210
	v_rsq_f32_e32 v189, v189
	v_pk_mul_f32 v[10:11], v[14:15], v[10:11]
	v_pk_mul_f32 v[12:13], v[16:17], v[12:13]
	v_pk_mul_f32 v[2:3], v[6:7], v[2:3]
	v_pk_mul_f32 v[4:5], v[8:9], v[4:5]
	v_mul_f32_e32 v150, 0xbfb8aa3b, v189
	v_mul_f32_e32 v152, v189, v189
	v_pk_mul_f32 v[130:131], v[14:15], v[150:151] op_sel_hi:[1,0]
	v_pk_mul_f32 v[132:133], v[16:17], v[150:151] op_sel_hi:[1,0]
	v_pk_mul_f32 v[134:135], v[6:7], v[150:151] op_sel_hi:[1,0]
	v_pk_mul_f32 v[136:137], v[8:9], v[150:151] op_sel_hi:[1,0]
	v_exp_f32_e32 v130, v130
	v_exp_f32_e32 v131, v131
	v_exp_f32_e32 v132, v132
	v_exp_f32_e32 v133, v133
	v_exp_f32_e32 v134, v134
	v_exp_f32_e32 v135, v135
	v_exp_f32_e32 v136, v136
	v_exp_f32_e32 v137, v137
	v_pk_add_f32 v[130:131], v[130:131], v[154:155]
	v_pk_add_f32 v[132:133], v[132:133], v[154:155]
	v_pk_add_f32 v[134:135], v[134:135], v[154:155]
	v_pk_add_f32 v[136:137], v[136:137], v[154:155]
	v_rcp_f32_e32 v130, v130
	v_rcp_f32_e32 v131, v131
	v_rcp_f32_e32 v132, v132
	v_rcp_f32_e32 v133, v133
	v_rcp_f32_e32 v134, v134
	v_rcp_f32_e32 v135, v135
	v_rcp_f32_e32 v136, v136
	v_rcp_f32_e32 v137, v137
	v_pk_mul_f32 v[130:131], v[130:131], v[152:153] op_sel_hi:[1,0]
	v_pk_mul_f32 v[132:133], v[132:133], v[152:153] op_sel_hi:[1,0]
	v_pk_mul_f32 v[134:135], v[134:135], v[152:153] op_sel_hi:[1,0]
	v_pk_mul_f32 v[136:137], v[136:137], v[152:153] op_sel_hi:[1,0]
	v_pk_mul_f32 v[10:11], v[10:11], v[130:131]
	v_pk_mul_f32 v[12:13], v[12:13], v[132:133]
	v_pk_mul_f32 v[2:3], v[2:3], v[134:135]
	v_pk_mul_f32 v[4:5], v[4:5], v[136:137]
	v_add_u32_e32 v157, 0xf2000, v156
	v_cvt_pk_bf16_f32 v184, v10, v11
	v_cvt_pk_bf16_f32 v185, v12, v13
	v_cvt_pk_bf16_f32 v186, v2, v3
	v_cvt_pk_bf16_f32 v187, v4, v5
	global_store_dwordx4 v157, v[184:187], s[18:19]
	s_branch .LBB0_186

; #define GAS __attribute__((address_space(1)))
; __device__ __forceinline__ u32x4 pack8(f32x4 a, f32x4 b) { u32x4 w; w.x = cvtpk(a[0], a[1]); w.y = cvtpk(a[2], a[3]); w.z = cvtpk(b[0], b[1]); w.w = cvtpk(b[2], b[3]); return w; }
; __device__ __forceinline__ f32x4 sig4(f32x4 x) { f32x4 r; r[0] = fsigmoid(x[0]); r[1] = fsigmoid(x[1]); r[2] = fsigmoid(x[2]); r[3] = fsigmoid(x[3]); return r; }
;     __device__ __forceinline__ void operator()(const f32x4 (&acc)[2][2][4][2], const Unit& u, int wr, int wc, int fr, int fq) const {
;     ...
;         if (mode == EM_SWIGLU) {
;             const int colh = u.pn * 128 + wc * 32 + fq * 8;
;             float rsv[2][4];
; #pragma unroll
;             for (int ai = 0; ai < 2; ++ai)
; #pragma unroll
;                 for (int m = 0; m < 4; ++m) rsv[ai][m] = ssq_in[rowb + ai * HALF + m * 16];
; #pragma unroll
;             for (int ai = 0; ai < 2; ++ai)
; #pragma unroll
;                 for (int m = 0; m < 4; ++m) {
;                     const int row = rowb + ai * HALF + m * 16;
;                     const float rstd = __builtin_amdgcn_rsqf(rsv[ai][m] * (1.0f / DM) + EPS);
;                     f32x4 o[2];
; #pragma unroll
;                     for (int n = 0; n < 2; ++n) { const f32x4 a = acc[ai][0][m][n] * rstd, g = acc[ai][1][m][n] * rstd; o[n] = a * sig4(a) * g; }
;                     *(GAS u32x4*)(o16 + (size_t)row * DFF + colh) = pack8(o[0], o[1]);
;                 }
.LBB0_555:
	s_cmp_eq_u32 s35, 4
	s_cbranch_scc1 .Lmerge_fast
	s_branch .Lstore_fast
.LBB0_711:
	s_branch .Lswiglu_fast
.LBB0_712:
	v_readlane_b32 s0, v246, 50
	v_readlane_b32 s1, v246, 51
	s_andn2_b64 vcc, exec, s[0:1]
	s_cbranch_vccnz .LBB0_169
	s_barrier
	s_branch .LBB0_169
